# attention: K/V tiles staged by LDS-DMA (source-side swizzle), K for the next item issued after QK and V after the item barrier; register staging and the ds_write burst removed
# speedup vs baseline: 1.0074x; 1.0058x over previous
; __device__ __forceinline__ AttItem att_decode(int I) {
;     AttItem t; const int bh = I / 48, it = I % 48; t.h = bh & 7; t.rowb = (size_t)(bh >> 3) * SEQ; int blk;
;     if (it < 16) { t.br = 0; t.r = 1; t.p = 0; blk = it; } else if (it < 32) { t.br = 1; t.r = 4; t.p = (it - 16) >> 2; blk = (it - 16) & 3; } else { t.br = 2; t.r = 16; t.p = it - 32; blk = 0; }
;     t.L = SEQ / t.r; t.idx0 = 128 * blk; return t;
; __device__ __forceinline__ void attn_phase(Frame& F, h16* Obr) {
;     ...
;     if (i_lo >= i_hi) return;
;     u32x4 kv[17]; h16x8 qn[4];
;     AttItem nx = att_decode(i_lo);
;     ATT_ISSUE(nx);
.LBB0_709:
	s_cmp_ge_i32 s14, s16
	s_cbranch_scc1 .LBB0_739
	v_readlane_b32 s100, v252, 7
	s_nop 3
	s_lshl_b32 s100, s100, 6
	s_add_u32 s101, s100, 0x10800
	s_mul_hi_i32 s0, s14, 0x2aaaaaab
	s_lshr_b32 s1, s0, 31
	s_ashr_i32 s0, s0, 3
	s_add_i32 s1, s0, s1
	s_mul_i32 s0, s1, 48
	s_sub_i32 s2, s14, s0
	s_cmp_lt_i32 s2, 16
	s_cbranch_scc1 .LBB0_715
	s_cmp_gt_u32 s2, 31
	s_mov_b64 s[22:23], -1
	s_cbranch_scc0 .LBB0_713
	s_sub_i32 s49, s2, 32
	s_mov_b64 s[22:23], 0

; __device__ __forceinline__ void attn_phase(Frame& F, h16* Obr) {
;     ...
;     AttItem nx = att_decode(i_lo);
;     ATT_ISSUE(nx);
.LBB0_719:
	v_readlane_b32 s4, v254, 42
	s_and_b32 s22, s1, 7
	s_lshl_b32 s51, s2, 7
	v_add_u32_e32 v73, s4, v70
	s_ashr_i32 s4, s1, 3
	s_ashr_i32 s5, s4, 31
	s_ff1_i32_b32 s1, s0
	s_lshl_b64 s[28:29], s[4:5], 11
	s_lshr_b32 s50, 0x800, s1
	v_ashrrev_i32_e32 v156, 4, v73
	s_lshl_b32 s1, s22, 7
	s_lshl_b32 s2, s22, 8
	v_readlane_b32 s4, v252, 3
	v_readlane_b32 s5, v252, 4
	s_add_u32 s4, s4, s2
	v_subrev_u32_e32 v157, 64, v156
	s_addc_u32 s5, s5, 0
	v_add_u32_e32 v72, s51, v157
	s_add_i32 s2, s50, -1
	v_and_b32_e32 v71, 15, v70
	v_min_i32_e32 v0, s2, v72
	v_cmp_lt_i32_e32 vcc, -1, v72
	v_lshlrev_b32_e32 v210, 2, v156
	v_and_b32_e32 v210, 12, v210
	v_bfe_u32 v211, v156, 2, 2
	v_or_b32_e32 v210, v210, v211
	v_xor_b32_e32 v210, v71, v210
	v_lshlrev_b32_e32 v208, 4, v210
	s_add_u32 s26, s28, s49
	v_cndmask_b32_e32 v0, 0, v0, vcc
	v_lshl_add_u64 v[68:69], s[4:5], 0, v[208:209]
	s_addc_u32 s27, s29, 0
	v_mul_lo_u32 v208, v0, s0
	v_lshl_add_u64 v[0:1], s[26:27], 0, v[208:209]
	v_mad_u64_u32 v[16:17], s[4:5], v0, s35, v[68:69]
	v_add_u32_e32 v0, 32, v72
	s_movk_i32 s4, 0xffdf
	v_min_i32_e32 v0, s2, v0
	v_cmp_lt_i32_e32 vcc, s4, v72
	v_add_u32_e32 v8, s51, v156
	v_min_i32_e32 v9, s2, v8
	v_cndmask_b32_e32 v0, 0, v0, vcc
	v_cmp_lt_i32_e32 vcc, -1, v8
	v_mul_lo_u32 v208, v0, s0
	v_mad_i32_i24 v17, v1, s35, v17
	v_cndmask_b32_e32 v8, 0, v9, vcc
	v_lshl_add_u64 v[0:1], s[26:27], 0, v[208:209]
	v_mul_lo_u32 v208, v8, s0
	v_lshl_add_u64 v[8:9], s[26:27], 0, v[208:209]
	v_mad_u64_u32 v[18:19], s[4:5], v0, s35, v[68:69]
	v_mad_u64_u32 v[44:45], s[4:5], v8, s35, v[68:69]
	v_add_u32_e32 v8, 0x60, v72
	s_movk_i32 s4, 0xff9f
	v_min_i32_e32 v8, s2, v8
	v_cmp_lt_i32_e32 vcc, s4, v72
	v_mad_i32_i24 v45, v9, s35, v45
	v_add_u32_e32 v20, 0x80, v72
	v_cndmask_b32_e32 v8, 0, v8, vcc
	v_mul_lo_u32 v208, v8, s0
	v_lshl_add_u64 v[8:9], s[26:27], 0, v[208:209]
	v_mad_u64_u32 v[46:47], s[4:5], v8, s35, v[68:69]
	s_movk_i32 s4, 0xff7f
	v_min_i32_e32 v20, s2, v20
	v_cmp_lt_i32_e32 vcc, s4, v72
	v_add_u32_e32 v28, 0xc0, v72
	v_min_i32_e32 v28, s2, v28
	v_cndmask_b32_e32 v20, 0, v20, vcc
	v_mul_lo_u32 v208, v20, s0
	v_lshl_add_u64 v[20:21], s[26:27], 0, v[208:209]
	v_mad_u64_u32 v[52:53], s[4:5], v20, s35, v[68:69]
	v_add_u32_e32 v20, 0xa0, v72
	s_movk_i32 s4, 0xff5f
	v_min_i32_e32 v20, s2, v20
	v_cmp_lt_i32_e32 vcc, s4, v72
	v_mad_i32_i24 v53, v21, s35, v53
	v_mad_i32_i24 v19, v1, s35, v19
	v_cndmask_b32_e32 v20, 0, v20, vcc
	v_mul_lo_u32 v208, v20, s0
	v_lshl_add_u64 v[20:21], s[26:27], 0, v[208:209]
	v_mad_u64_u32 v[54:55], s[4:5], v20, s35, v[68:69]
	s_movk_i32 s4, 0xff3f
	s_nop 0
	v_cmp_lt_i32_e32 vcc, s4, v72
	s_add_u32 m0, s100, 0x0
	s_nop 0
	global_load_lds_dwordx4 v[16:17], off offset:2048
	s_add_u32 m0, s100, 0x2000
	s_nop 0
	global_load_lds_dwordx4 v[18:19], off offset:2048
	v_cndmask_b32_e32 v28, 0, v28, vcc
	v_mul_lo_u32 v208, v28, s0
	v_lshl_add_u64 v[28:29], s[26:27], 0, v[208:209]
	v_mad_u64_u32 v[60:61], s[4:5], v28, s35, v[68:69]
	v_add_u32_e32 v28, 0xe0, v72
	s_movk_i32 s4, 0xff1f
	v_min_i32_e32 v28, s2, v28
	v_cmp_lt_i32_e32 vcc, s4, v72
	v_mad_i32_i24 v61, v29, s35, v61
	v_mad_i32_i24 v47, v9, s35, v47
	v_cndmask_b32_e32 v28, 0, v28, vcc
	v_mul_lo_u32 v208, v28, s0
	v_lshl_add_u64 v[28:29], s[26:27], 0, v[208:209]
	v_mad_u64_u32 v[62:63], s[4:5], v28, s35, v[68:69]
	s_movk_i32 s4, 0x1000
	s_nop 0
	v_add_co_u32_e32 v16, vcc, s4, v16
	s_add_u32 m0, s100, 0x4000
	s_nop 0
	global_load_lds_dwordx4 v[44:45], off offset:2048
	s_add_u32 m0, s100, 0x6000
	s_nop 0
	global_load_lds_dwordx4 v[46:47], off offset:2048
	v_addc_co_u32_e32 v17, vcc, 0, v17, vcc
	v_add_co_u32_e32 v18, vcc, s4, v18
	v_mad_i32_i24 v55, v21, s35, v55
	s_nop 0
	v_addc_co_u32_e32 v19, vcc, 0, v19, vcc
	s_add_u32 m0, s100, 0x8000
	s_nop 0
	global_load_lds_dwordx4 v[52:53], off offset:2048
	s_add_u32 m0, s100, 0xa000
	s_nop 0
	global_load_lds_dwordx4 v[54:55], off offset:2048
	v_mad_i32_i24 v63, v29, s35, v63
	s_add_u32 m0, s100, 0xc000
	s_nop 0
	global_load_lds_dwordx4 v[60:61], off offset:2048
	s_add_u32 m0, s100, 0xe000
	s_nop 0
	global_load_lds_dwordx4 v[62:63], off offset:2048
	v_mov_b64_e32 v[36:37], v[16:17]
	v_mov_b64_e32 v[40:41], v[18:19]
	v_add_co_u32_e32 v16, vcc, s4, v44
	s_nop 1
	v_addc_co_u32_e32 v17, vcc, 0, v45, vcc
	v_add_co_u32_e32 v18, vcc, s4, v46
	s_nop 1
	v_addc_co_u32_e32 v19, vcc, 0, v47, vcc
	v_mov_b64_e32 v[44:45], v[16:17]
	v_mov_b64_e32 v[48:49], v[18:19]
	v_add_co_u32_e32 v16, vcc, s4, v52
	s_nop 1
	v_addc_co_u32_e32 v17, vcc, 0, v53, vcc
	v_add_co_u32_e32 v18, vcc, s4, v54
	s_movk_i32 s4, 0x100
	s_nop 0
	v_addc_co_u32_e32 v19, vcc, 0, v55, vcc
	v_mov_b64_e32 v[52:53], v[16:17]
	v_mov_b64_e32 v[56:57], v[18:19]
	v_add_co_u32_e32 v16, vcc, 0x1000, v60
	v_cmp_gt_i32_e64 s[36:37], s4, v73
	s_nop 0
	v_addc_co_u32_e32 v17, vcc, 0, v61, vcc
	v_add_co_u32_e32 v18, vcc, 0x1000, v62
	s_nop 1
	v_addc_co_u32_e32 v19, vcc, 0, v63, vcc
	v_mov_b64_e32 v[60:61], v[16:17]
	v_mov_b64_e32 v[64:65], v[18:19]
	s_and_saveexec_b64 s[38:39], s[36:37]
	s_cbranch_execz .LBB0_721
	v_add_u32_e32 v16, 0x100, v72
	v_min_i32_e32 v16, s2, v16
	s_movk_i32 s2, 0xfeff
	v_cmp_lt_i32_e32 vcc, s2, v72
	s_nop 1
	v_cndmask_b32_e32 v16, 0, v16, vcc
	v_mul_lo_u32 v208, v16, s0
	v_lshl_add_u64 v[16:17], s[26:27], 0, v[208:209]
	v_mad_u64_u32 v[18:19], s[4:5], v16, s35, v[68:69]
	v_mad_i32_i24 v17, v17, s35, v19
	v_add_co_u32_e32 v16, vcc, 0x1000, v18
	s_nop 1
	v_addc_co_u32_e32 v17, vcc, 0, v17, vcc
; #define LAS __attribute__((address_space(3)))
; __device__ __forceinline__ void attn_phase(Frame& F, h16* Obr) {
;     ...
;         {   const int ch = tid & 15, r4 = tid >> 4;
; #pragma unroll
;             for (int j = 0; j < 17; ++j) { const bool isv = j >= 8; const int rr = isv ? r4 + 32 * (j - 8) : r4 + 32 * j;
;                 if (j < 16 || tid < 256) *(LAS u32x4*)(lds + (isv ? ATT_V : ATT_K) + att_off(rr, ch)) = kv[j]; } }
;         h16x8 Qf[4];
; #pragma unroll
;         for (int s = 0; s < 4; ++s) Qf[s] = qn[s];
;         __syncthreads();
;         if (I + i_st < i_hi) { nx = att_decode(I + i_st); ATT_ISSUE(nx); }
;         const int idx0 = cu.idx0, L = cu.L;
;         const int qtok = cu.p + cu.r * (idx0 + 16 * w + q16);
;         f32x4 sc[9];
;         h16x8 kfb[2][4];
; #pragma unroll
;         for (int s = 0; s < 4; ++s) kfb[0][s] = *(const LAS h16x8*)(lds + ATT_K + att_off(16 * w + q16, 4 * s + g));
.LBB0_721:
	s_or_b64 exec, exec, s[38:39]
	v_readlane_b32 s6, v252, 7
	v_lshlrev_b32_e32 v69, 3, v71
	s_add_i32 s2, s51, s6
	v_lshlrev_b32_e32 v208, 1, v69
	v_or_b32_e32 v69, s2, v71
	v_mul_lo_u32 v69, v69, s0
	v_readlane_b32 s4, v252, 3
	v_add_u32_e32 v72, s49, v69
	v_readlane_b32 s5, v252, 4
	v_ashrrev_i32_e32 v73, 31, v72
	v_lshl_add_u64 v[72:73], s[28:29], 0, v[72:73]
	v_mov_b64_e32 v[74:75], s[4:5]
	v_lshlrev_b32_e32 v210, 2, v156
	v_and_b32_e32 v210, 12, v210
	v_bfe_u32 v211, v156, 2, 2
	v_or_b32_e32 v210, v210, v211
	v_xor_b32_e32 v210, v71, v210
	v_lshlrev_b32_e32 v210, 4, v210
	v_mov_b32_e32 v211, 0
	v_lshl_add_u64 v[148:149], s[4:5], 0, v[210:211]
	v_mad_u64_u32 v[74:75], s[4:5], v72, s35, v[74:75]
	v_bfe_u32 v76, v70, 4, 2
	v_mad_i32_i24 v75, v73, s35, v75
	s_lshl_b32 s2, s1, 1
	v_lshl_add_u64 v[72:73], v[74:75], 0, s[2:3]
	v_lshlrev_b32_e32 v208, 4, v76
	v_lshl_add_u64 v[72:73], v[72:73], 0, v[208:209]
	global_load_dwordx4 v[84:87], v[72:73], off offset:192
	global_load_dwordx4 v[88:91], v[72:73], off offset:128
	global_load_dwordx4 v[92:95], v[72:73], off offset:64
	global_load_dwordx4 v[96:99], v[72:73], off
	v_lshlrev_b32_e32 v69, 2, v156
	v_and_b32_e32 v69, 12, v69
	v_bfe_u32 v72, v156, 2, 2
	v_bitop3_b32 v69, v69, v71, v72 bitop3:0x36
	v_lshl_add_u32 v159, v69, 4, 0
	v_lshlrev_b32_e32 v69, 2, v71
	v_and_b32_e32 v69, 12, v69
	v_bfe_u32 v72, v70, 2, 2
	v_bitop3_b32 v105, v69, v76, v72 bitop3:0x36
	v_lshlrev_b32_e32 v164, 4, v105
	v_add_u32_e32 v164, 0x800, v164
	v_or_b32_e32 v105, 4, v76
	v_lshlrev_b32_e32 v150, 2, v76
	v_bfe_u32 v74, v70, 1, 1
	v_and_b32_e32 v75, 12, v70
	v_bitop3_b32 v105, v69, v105, v72 bitop3:0x36
	v_lshlrev_b32_e32 v68, 3, v76
	v_or_b32_e32 v162, s6, v150
	v_lshrrev_b32_e32 v73, 2, v71
	v_or_b32_e32 v77, v76, v75
	v_bitop3_b32 v75, v76, v74, v75 bitop3:0x36
	v_cmp_eq_u32_e64 s[38:39], 0, v76
	v_lshlrev_b32_e32 v165, 4, v105
	v_add_u32_e32 v165, 0x800, v165
	v_or_b32_e32 v105, 8, v76
	v_or_b32_e32 v76, 12, v76
	v_or_b32_e32 v73, v162, v73
	s_add_i32 s1, 0, 0x10800
	v_lshlrev_b32_e32 v70, 3, v70
	v_bitop3_b32 v105, v69, v105, v72 bitop3:0x36
	v_bitop3_b32 v69, v69, v76, v72 bitop3:0x36
	v_lshl_add_u32 v75, v75, 4, s1
	v_and_b32_e32 v70, 8, v70
	v_lshlrev_b32_e32 v167, 4, v69
	v_add_u32_e32 v167, 0x800, v167
	v_readlane_b32 s2, v252, 8
	v_lshlrev_b32_e32 v69, 8, v73
	v_or_b32_e32 v158, s6, v71
	v_add_u32_e32 v78, v75, v70
	v_lshlrev_b32_e32 v166, 4, v105
	v_add_u32_e32 v166, 0x800, v166
	v_lshl_add_u32 v168, v71, 8, s2
	v_add_u32_e32 v71, v75, v69
	v_bitop3_b32 v72, v74, v77, 2 bitop3:0x36
	v_bitop3_b32 v75, v74, v77, 4 bitop3:0x36
	v_bitop3_b32 v105, v74, v77, 6 bitop3:0x36
	v_bitop3_b32 v107, v74, v77, 8 bitop3:0x36
	v_bitop3_b32 v109, v74, v77, 10 bitop3:0x36
	v_bitop3_b32 v111, v74, v77, 12 bitop3:0x36
	v_bitop3_b32 v74, v74, v77, 14 bitop3:0x36
	v_add_u32_e32 v79, s1, v70
	v_lshlrev_b32_e32 v72, 4, v72
	v_lshlrev_b32_e32 v75, 4, v75
	v_lshlrev_b32_e32 v105, 4, v105
	v_lshlrev_b32_e32 v107, 4, v107
	v_lshlrev_b32_e32 v109, 4, v109
	v_lshlrev_b32_e32 v111, 4, v111
	v_lshlrev_b32_e32 v74, 4, v74
	v_lshlrev_b32_e32 v163, 8, v156
	v_add_u32_e32 v80, 0x10000, v159
	v_add_u32_e32 v81, 0x12000, v159
	v_add_u32_e32 v82, 0x14000, v159
	v_add_u32_e32 v83, 0x16000, v159
	v_add_u32_e32 v100, 0x18000, v159
	v_add_u32_e32 v101, 0x1a000, v159
	v_add_u32_e32 v102, 0x1c000, v159
	v_add_u32_e32 v103, 0x1e000, v159
	v_add_u32_e32 v104, 0x20000, v159
	v_add_u32_e32 v73, v79, v72
	v_add3_u32 v72, s1, v72, v69
	v_add_u32_e32 v76, v79, v75
	v_add3_u32 v75, s1, v75, v69
	v_add_u32_e32 v106, v79, v105
	v_add3_u32 v105, s1, v105, v69
	v_add_u32_e32 v108, v79, v107
	v_add3_u32 v107, s1, v107, v69
	v_add_u32_e32 v110, v79, v109
	v_add3_u32 v109, s1, v109, v69
	v_add_u32_e32 v112, v79, v111
	v_add3_u32 v111, s1, v111, v69
	v_add_u32_e32 v77, v79, v74
	v_add3_u32 v74, s1, v74, v69
	v_lshl_add_u32 v160, v158, 8, 0
	v_add_u32_e32 v161, 0x80, v158
	v_mov_b32_e32 v151, v209
	s_add_i32 s17, s14, s15
	v_add_u32_e32 v169, v80, v163
	v_add_u32_e32 v170, v81, v163
	v_add_u32_e32 v171, v82, v163
	v_add_u32_e32 v172, v83, v163
	v_add_u32_e32 v173, v100, v163
	v_add_u32_e32 v174, v101, v163
	v_add_u32_e32 v175, v102, v163
	v_add_u32_e32 v176, v103, v163
	v_add_u32_e32 v177, v104, v163
	v_lshlrev_b32_e32 v208, 1, v68
	v_add_u32_e32 v178, v78, v69
	v_add_u32_e32 v179, v71, v70
	v_add_u32_e32 v180, v73, v69
	v_add_u32_e32 v181, v72, v70
	v_add_u32_e32 v182, v76, v69
	v_add_u32_e32 v183, v75, v70
	v_add_u32_e32 v184, v106, v69
	v_add_u32_e32 v185, v105, v70
	v_add_u32_e32 v186, v108, v69
	v_add_u32_e32 v187, v107, v70
	v_add_u32_e32 v188, v110, v69
	v_add_u32_e32 v189, v109, v70
	v_add_u32_e32 v190, v112, v69
	v_add_u32_e32 v191, v111, v70
	v_add_u32_e32 v192, v77, v69
	v_add_u32_e32 v193, v74, v70
	s_waitcnt vmcnt(0)
	s_branch .LBB0_723

; #define LAS __attribute__((address_space(3)))
; __device__ __forceinline__ void attn_phase(Frame& F, h16* Obr) {
;     ...
;     for (int I = i_lo; I < i_hi; I += i_st) {
;         const AttItem cu = nx;
;         __syncthreads();
;         {   const int ch = tid & 15, r4 = tid >> 4;
; #pragma unroll
;             for (int j = 0; j < 17; ++j) { const bool isv = j >= 8; const int rr = isv ? r4 + 32 * (j - 8) : r4 + 32 * j;
;                 if (j < 16 || tid < 256) *(LAS u32x4*)(lds + (isv ? ATT_V : ATT_K) + att_off(rr, ch)) = kv[j]; } }
;         h16x8 Qf[4];
; #pragma unroll
;         for (int s = 0; s < 4; ++s) Qf[s] = qn[s];
;         __syncthreads();
;         if (I + i_st < i_hi) { nx = att_decode(I + i_st); ATT_ISSUE(nx); }
;         const int idx0 = cu.idx0, L = cu.L;
;         const int qtok = cu.p + cu.r * (idx0 + 16 * w + q16);
;         f32x4 sc[9];
;         h16x8 kfb[2][4];
; #pragma unroll
;         for (int s = 0; s < 4; ++s) kfb[0][s] = *(const LAS h16x8*)(lds + ATT_K + att_off(16 * w + q16, 4 * s + g));
; #pragma unroll
;         for (int tt = 0; tt < 9; ++tt) {
;             if (tt + 1 < 9) {
; #pragma unroll
;                 for (int s = 0; s < 4; ++s) kfb[(tt + 1) & 1][s] = *(const LAS h16x8*)(lds + ATT_K + att_off(16 * (w + tt + 1) + q16, 4 * s + g)); }
;             asm volatile("" ::: "memory");
;             f32x4 a = {0.f, 0.f, 0.f, 0.f};
; #pragma unroll
;             for (int s = 0; s < 4; ++s) a = __builtin_amdgcn_mfma_f32_16x16x32_f16(kfb[tt & 1][s], Qf[s], a, 0, 0, 0);
;             sc[tt] = a; }
.LBB0_723:
	s_waitcnt vmcnt(63) expcnt(7) lgkmcnt(15)
	s_barrier
	s_add_u32 m0, s101, 0x0
	s_nop 0
	global_load_lds_dwordx4 v[36:37], off
	s_add_u32 m0, s101, 0x2000
	s_nop 0
	global_load_lds_dwordx4 v[40:41], off
	s_add_u32 m0, s101, 0x4000
	s_nop 0
	global_load_lds_dwordx4 v[44:45], off
	s_add_u32 m0, s101, 0x6000
	s_nop 0
	global_load_lds_dwordx4 v[48:49], off
	s_add_u32 m0, s101, 0x8000
	s_nop 0
	global_load_lds_dwordx4 v[52:53], off
	s_add_u32 m0, s101, 0xa000
	s_nop 0
	global_load_lds_dwordx4 v[56:57], off
	s_add_u32 m0, s101, 0xc000
	s_nop 0
	global_load_lds_dwordx4 v[60:61], off
	s_add_u32 m0, s101, 0xe000
	s_nop 0
	global_load_lds_dwordx4 v[64:65], off
	s_and_saveexec_b64 s[26:27], s[36:37]
	s_cbranch_execz .Lattn_v17
	s_add_u32 m0, s101, 0x10000
	s_nop 0
	global_load_lds_dwordx4 v[16:17], off
.Lattn_v17:
	s_or_b64 exec, exec, s[26:27]
	s_branch .LBB0_737
.LBB0_737:
	v_add_u32_e32 v100, s51, v158
	v_mul_lo_u32 v128, s0, v100
	v_add_u32_e32 v100, v160, v164
	ds_read_b128 v[100:103], v100
	v_add_u32_e32 v104, v160, v165
	ds_read_b128 v[104:107], v104
	v_add_u32_e32 v108, v160, v166
	ds_read_b128 v[108:111], v108
	v_add_u32_e32 v129, v168, v164
	ds_read_b128 v[116:119], v129 offset:4096
	v_add_u32_e32 v112, v160, v167
	s_waitcnt vmcnt(20) lgkmcnt(3)
	v_mfma_f32_16x16x32_f16 v[100:103], v[100:103], v[96:99], 0
	ds_read_b128 v[112:115], v112
	v_add_u32_e32 v146, v168, v165
	ds_read_b128 v[120:123], v146 offset:4096
	s_waitcnt lgkmcnt(4)
	v_mfma_f32_16x16x32_f16 v[100:103], v[104:107], v[92:95], v[100:103]
	v_add_u32_e32 v147, v168, v166
	ds_read_b128 v[124:127], v147 offset:4096
	v_add_u32_e32 v206, v168, v167
	s_waitcnt lgkmcnt(4)
	v_mfma_f32_16x16x32_f16 v[100:103], v[108:111], v[88:91], v[100:103]
	ds_read_b128 v[130:133], v206 offset:4096
	s_waitcnt lgkmcnt(4)
	v_mfma_f32_16x16x32_f16 v[104:107], v[116:119], v[96:99], 0
	s_waitcnt lgkmcnt(3)
	v_mfma_f32_16x16x32_f16 v[100:103], v[112:115], v[84:87], v[100:103]
	ds_read_b128 v[108:111], v129 offset:8192
	ds_read_b128 v[112:115], v146 offset:8192
	ds_read_b128 v[134:137], v147 offset:8192
	ds_read_b128 v[138:141], v206 offset:8192
	s_waitcnt lgkmcnt(6)
	v_mfma_f32_16x16x32_f16 v[104:107], v[120:123], v[92:95], v[104:107]
	s_waitcnt lgkmcnt(3)
	v_mfma_f32_16x16x32_f16 v[108:111], v[108:111], v[96:99], 0
	v_mfma_f32_16x16x32_f16 v[104:107], v[124:127], v[88:91], v[104:107]
	s_waitcnt lgkmcnt(2)
	v_mfma_f32_16x16x32_f16 v[108:111], v[112:115], v[92:95], v[108:111]
	v_mfma_f32_16x16x32_f16 v[104:107], v[130:133], v[84:87], v[104:107]
	ds_read_b128 v[116:119], v129 offset:12288
	ds_read_b128 v[120:123], v146 offset:12288
	ds_read_b128 v[124:127], v147 offset:12288
	ds_read_b128 v[130:133], v206 offset:12288
	s_waitcnt lgkmcnt(5)
	v_mfma_f32_16x16x32_f16 v[108:111], v[134:137], v[88:91], v[108:111]
	s_waitcnt lgkmcnt(3)
	v_mfma_f32_16x16x32_f16 v[112:115], v[116:119], v[96:99], 0
	v_mfma_f32_16x16x32_f16 v[108:111], v[138:141], v[84:87], v[108:111]
	ds_read_b128 v[134:137], v129 offset:16384
	ds_read_b128 v[138:141], v146 offset:16384
	ds_read_b128 v[142:145], v147 offset:16384
	ds_read_b128 v[152:155], v206 offset:16384
	s_waitcnt lgkmcnt(6)
	v_mfma_f32_16x16x32_f16 v[112:115], v[120:123], v[92:95], v[112:115]
	s_waitcnt lgkmcnt(3)
	v_mfma_f32_16x16x32_f16 v[116:119], v[134:137], v[96:99], 0
	v_mfma_f32_16x16x32_f16 v[112:115], v[124:127], v[88:91], v[112:115]
	s_waitcnt lgkmcnt(2)
	v_mfma_f32_16x16x32_f16 v[116:119], v[138:141], v[92:95], v[116:119]
	v_mfma_f32_16x16x32_f16 v[112:115], v[130:133], v[84:87], v[112:115]
	ds_read_b128 v[120:123], v129 offset:20480
	ds_read_b128 v[124:127], v146 offset:20480
	ds_read_b128 v[130:133], v147 offset:20480
	ds_read_b128 v[194:197], v206 offset:20480
	s_waitcnt lgkmcnt(5)
	v_mfma_f32_16x16x32_f16 v[116:119], v[142:145], v[88:91], v[116:119]
	s_waitcnt lgkmcnt(3)
	v_mfma_f32_16x16x32_f16 v[120:123], v[120:123], v[96:99], 0
	v_mfma_f32_16x16x32_f16 v[116:119], v[152:155], v[84:87], v[116:119]
	ds_read_b128 v[134:137], v129 offset:24576
	ds_read_b128 v[138:141], v146 offset:24576
	ds_read_b128 v[142:145], v147 offset:24576
	ds_read_b128 v[152:155], v206 offset:24576
	s_waitcnt lgkmcnt(6)
	v_mfma_f32_16x16x32_f16 v[120:123], v[124:127], v[92:95], v[120:123]
	s_waitcnt lgkmcnt(3)
	v_mfma_f32_16x16x32_f16 v[124:127], v[134:137], v[96:99], 0
	s_waitcnt lgkmcnt(2)
	v_mfma_f32_16x16x32_f16 v[124:127], v[138:141], v[92:95], v[124:127]
	v_mfma_f32_16x16x32_f16 v[120:123], v[130:133], v[88:91], v[120:123]
	s_waitcnt lgkmcnt(1)
	v_mfma_f32_16x16x32_f16 v[124:127], v[142:145], v[88:91], v[124:127]
	v_mfma_f32_16x16x32_f16 v[120:123], v[194:197], v[84:87], v[120:123]
	ds_read_b128 v[130:133], v129 offset:28672
	ds_read_b128 v[194:197], v146 offset:28672
	ds_read_b128 v[198:201], v147 offset:28672
	ds_read_b128 v[202:205], v206 offset:28672
	s_waitcnt lgkmcnt(4)
	v_mfma_f32_16x16x32_f16 v[124:127], v[152:155], v[84:87], v[124:127]
	ds_read_b128 v[134:137], v129 offset:32768
	ds_read_b128 v[138:141], v146 offset:32768
	ds_read_b128 v[142:145], v147 offset:32768
	ds_read_b128 v[152:155], v206 offset:32768
	s_waitcnt lgkmcnt(7)
	v_mfma_f32_16x16x32_f16 v[130:133], v[130:133], v[96:99], 0
	s_waitcnt lgkmcnt(3)
	v_mfma_f32_16x16x32_f16 v[96:99], v[134:137], v[96:99], 0
	v_mfma_f32_16x16x32_f16 v[130:133], v[194:197], v[92:95], v[130:133]
	s_waitcnt lgkmcnt(2)
	v_mfma_f32_16x16x32_f16 v[92:95], v[138:141], v[92:95], v[96:99]
	v_mfma_f32_16x16x32_f16 v[130:133], v[198:201], v[88:91], v[130:133]
	s_waitcnt lgkmcnt(1)
	v_mfma_f32_16x16x32_f16 v[88:91], v[142:145], v[88:91], v[92:95]
	v_mfma_f32_16x16x32_f16 v[130:133], v[202:205], v[84:87], v[130:133]
	s_waitcnt lgkmcnt(0)
	v_mfma_f32_16x16x32_f16 v[84:87], v[152:155], v[84:87], v[88:91]
	s_cmp_ge_i32 s17, s16
	s_waitcnt vmcnt(0) lgkmcnt(0)
	s_barrier
	s_cbranch_scc1 .LBB0_731
	s_mul_hi_i32 s1, s17, 0x2aaaaaab
	s_lshr_b32 s2, s1, 31
	s_ashr_i32 s1, s1, 3
	s_add_i32 s1, s1, s2
	s_mul_i32 s2, s1, 0xffffffd0
	s_add_i32 s2, s17, s2
	s_cmp_lt_i32 s2, 16
	s_cbranch_scc1 .LBB0_732
	s_cmp_gt_u32 s2, 31
	s_mov_b64 s[26:27], -1
	s_cbranch_scc0 .LBB0_729
	s_sub_i32 s19, s2, 32
	s_mov_b64 s[26:27], 0

; __device__ __forceinline__ void attn_phase(Frame& F, h16* Obr) {
;     ...
;         if (I + i_st < i_hi) { nx = att_decode(I + i_st); ATT_ISSUE(nx); }
.LBB0_734:
	s_ashr_i32 s4, s1, 3
	s_and_b32 s46, s1, 7
	s_ff1_i32_b32 s1, s45
	s_lshr_b32 s47, 0x800, s1
	s_lshl_b32 s48, s2, 7
	v_add_u32_e32 v70, s48, v157
	s_add_i32 s1, s47, -1
	s_ashr_i32 s5, s4, 31
	v_min_i32_e32 v0, s1, v70
	v_cmp_lt_i32_e32 vcc, -1, v70
	s_lshl_b64 s[26:27], s[4:5], 11
	s_lshl_b32 s2, s46, 8
	v_cndmask_b32_e32 v0, 0, v0, vcc
	s_add_u32 s40, s26, s19
	v_mul_lo_u32 v0, v0, s45
	s_addc_u32 s41, s27, 0
	v_ashrrev_i32_e32 v1, 31, v0
	v_lshl_add_u64 v[68:69], v[148:149], 0, s[2:3]
	v_lshl_add_u64 v[0:1], s[40:41], 0, v[0:1]
	v_mad_u64_u32 v[36:37], s[4:5], v0, s35, v[68:69]
	v_add_u32_e32 v0, 32, v70
	s_movk_i32 s2, 0xffdf
	v_min_i32_e32 v0, s1, v0
	v_cmp_lt_i32_e32 vcc, s2, v70
	v_add_u32_e32 v8, s48, v156
	v_min_i32_e32 v9, s1, v8
	v_cndmask_b32_e32 v0, 0, v0, vcc
	v_cmp_lt_i32_e32 vcc, -1, v8
	s_movk_i32 s2, 0xff9f
	v_add_u32_e32 v20, 0x80, v70
	v_cndmask_b32_e32 v8, 0, v9, vcc
	v_mul_lo_u32 v8, v8, s45
	v_ashrrev_i32_e32 v9, 31, v8
	v_lshl_add_u64 v[8:9], s[40:41], 0, v[8:9]
	v_mad_u64_u32 v[44:45], s[4:5], v8, s35, v[68:69]
	v_add_u32_e32 v8, 0x60, v70
	v_min_i32_e32 v8, s1, v8
	v_cmp_lt_i32_e32 vcc, s2, v70
	s_movk_i32 s2, 0xff7f
	v_min_i32_e32 v20, s1, v20
	v_cndmask_b32_e32 v8, 0, v8, vcc
	v_cmp_lt_i32_e32 vcc, s2, v70
	s_movk_i32 s2, 0xff5f
	v_add_u32_e32 v28, 0xc0, v70
	v_cndmask_b32_e32 v20, 0, v20, vcc
	v_mul_lo_u32 v20, v20, s45
	v_ashrrev_i32_e32 v21, 31, v20
	v_lshl_add_u64 v[20:21], s[40:41], 0, v[20:21]
	v_mad_u64_u32 v[52:53], s[4:5], v20, s35, v[68:69]
	v_add_u32_e32 v20, 0xa0, v70
	v_min_i32_e32 v20, s1, v20
	v_cmp_lt_i32_e32 vcc, s2, v70
	s_movk_i32 s2, 0xff3f
	v_min_i32_e32 v28, s1, v28
	v_cndmask_b32_e32 v20, 0, v20, vcc
	v_cmp_lt_i32_e32 vcc, s2, v70
	v_mul_lo_u32 v0, v0, s45
	v_mad_i32_i24 v37, v1, s35, v37
	v_cndmask_b32_e32 v28, 0, v28, vcc
	v_mul_lo_u32 v28, v28, s45
	v_ashrrev_i32_e32 v29, 31, v28
	v_ashrrev_i32_e32 v1, 31, v0
	v_lshl_add_u64 v[28:29], s[40:41], 0, v[28:29]
	v_lshl_add_u64 v[0:1], s[40:41], 0, v[0:1]
	v_mad_u64_u32 v[60:61], s[4:5], v28, s35, v[68:69]
	v_add_u32_e32 v28, 0xe0, v70
	s_movk_i32 s2, 0xff1f
	v_mad_u64_u32 v[38:39], s[4:5], v0, s35, v[68:69]
	v_min_i32_e32 v28, s1, v28
	v_cmp_lt_i32_e32 vcc, s2, v70
	s_movk_i32 s2, 0x1000
	v_mad_i32_i24 v39, v1, s35, v39
	s_add_u32 m0, s100, 0x0
	s_nop 0
	global_load_lds_dwordx4 v[36:37], off offset:2048
	s_add_u32 m0, s100, 0x2000
	s_nop 0
	global_load_lds_dwordx4 v[38:39], off offset:2048
	v_mul_lo_u32 v8, v8, s45
	v_cndmask_b32_e32 v28, 0, v28, vcc
	v_add_co_u32_e32 v36, vcc, s2, v36
	v_mad_i32_i24 v45, v9, s35, v45
	v_ashrrev_i32_e32 v9, 31, v8
	v_addc_co_u32_e32 v37, vcc, 0, v37, vcc
	v_lshl_add_u64 v[8:9], s[40:41], 0, v[8:9]
	v_add_co_u32_e32 v40, vcc, s2, v38
	v_mad_u64_u32 v[46:47], s[4:5], v8, s35, v[68:69]
	s_nop 0
	v_addc_co_u32_e32 v41, vcc, 0, v39, vcc
	v_mad_i32_i24 v47, v9, s35, v47
	s_add_u32 m0, s100, 0x4000
	s_nop 0
	global_load_lds_dwordx4 v[44:45], off offset:2048
	s_add_u32 m0, s100, 0x6000
	s_nop 0
	global_load_lds_dwordx4 v[46:47], off offset:2048
	v_mul_lo_u32 v20, v20, s45
	v_add_co_u32_e32 v44, vcc, s2, v44
	v_mad_i32_i24 v53, v21, s35, v53
	v_ashrrev_i32_e32 v21, 31, v20
	v_addc_co_u32_e32 v45, vcc, 0, v45, vcc
	v_lshl_add_u64 v[20:21], s[40:41], 0, v[20:21]
	v_add_co_u32_e32 v48, vcc, s2, v46
	v_mad_u64_u32 v[54:55], s[4:5], v20, s35, v[68:69]
	s_nop 0
	v_addc_co_u32_e32 v49, vcc, 0, v47, vcc
	v_mad_i32_i24 v55, v21, s35, v55
	s_add_u32 m0, s100, 0x8000
	s_nop 0
	global_load_lds_dwordx4 v[52:53], off offset:2048
	s_add_u32 m0, s100, 0xa000
	s_nop 0
	global_load_lds_dwordx4 v[54:55], off offset:2048
	v_mul_lo_u32 v28, v28, s45
	v_add_co_u32_e32 v52, vcc, s2, v52
	v_mad_i32_i24 v61, v29, s35, v61
	v_ashrrev_i32_e32 v29, 31, v28
	v_addc_co_u32_e32 v53, vcc, 0, v53, vcc
	v_lshl_add_u64 v[28:29], s[40:41], 0, v[28:29]
	v_add_co_u32_e32 v56, vcc, s2, v54
	v_mad_u64_u32 v[62:63], s[4:5], v28, s35, v[68:69]
	s_nop 0
	v_addc_co_u32_e32 v57, vcc, 0, v55, vcc
	v_mad_i32_i24 v63, v29, s35, v63
	s_add_u32 m0, s100, 0xc000
	s_nop 0
	global_load_lds_dwordx4 v[60:61], off offset:2048
	s_add_u32 m0, s100, 0xe000
	s_nop 0
	global_load_lds_dwordx4 v[62:63], off offset:2048
	v_add_co_u32_e32 v60, vcc, 0x1000, v60
	s_nop 0
	v_addc_co_u32_e32 v61, vcc, 0, v61, vcc
	v_add_co_u32_e32 v64, vcc, 0x1000, v62
	s_nop 0
	v_addc_co_u32_e32 v65, vcc, 0, v63, vcc
	s_nop 0
	s_nop 0
	s_nop 0
	s_and_saveexec_b64 s[42:43], s[36:37]
	s_cbranch_execz .LBB0_736
	v_add_u32_e32 v16, 0x100, v70
	v_min_i32_e32 v16, s1, v16
	s_movk_i32 s1, 0xfeff
	v_cmp_lt_i32_e32 vcc, s1, v70
	s_nop 1
	v_cndmask_b32_e32 v16, 0, v16, vcc
	v_mul_lo_u32 v16, v16, s45
	v_ashrrev_i32_e32 v17, 31, v16
	v_lshl_add_u64 v[16:17], s[40:41], 0, v[16:17]
	v_mad_u64_u32 v[18:19], s[4:5], v16, s35, v[68:69]
	v_mad_i32_i24 v17, v17, s35, v19
	v_add_co_u32_e32 v16, vcc, 0x1000, v18
	s_nop 1
	v_addc_co_u32_e32 v17, vcc, 0, v17, vcc

; __device__ __forceinline__ void attn_phase(Frame& F, h16* Obr) {
;     ...
;         const int ql = 16 * w + q16;
;         const int clo = ql > 64 - idx0 ? ql : 64 - idx0, chi = (ql + 128) < (L + 63 - idx0) ? (ql + 128) : (L + 63 - idx0);
;         const unsigned span = (unsigned)(chi - clo); const int cb = 16 * w + 4 * g - clo;
;         float mx = -3.0e38f;
; #pragma unroll
;         for (int tt = 0; tt < 9; ++tt)
; #pragma unroll
;             for (int e = 0; e < 4; ++e) { const bool ok = (unsigned)(cb + 16 * tt + e) <= span; sc[tt][e] = ok ? sc[tt][e] : -3.0e38f; mx = fmaxf(mx, sc[tt][e]); }
;         mx = fmaxf(mx, shx<16>(mx)); mx = fmaxf(mx, shx<32>(mx));
.Lattn_sm:
	s_sub_i32 s0, 64, s51
	s_mul_hi_u32 s1, s23, 0xc000
	v_readlane_b32 s4, v251, 0
	v_readlane_b32 s6, v251, 2
	v_readlane_b32 s7, v251, 3
	v_readlane_b32 s5, v251, 1
	s_nop 3
	s_nop 4
	v_max_i32_e32 v88, s0, v158
	s_sub_i32 s0, s50, s51
	s_add_i32 s0, s0, 63
	v_min_i32_e32 v89, s0, v161
	v_sub_u32_e32 v89, v89, v88
	v_sub_u32_e32 v88, v162, v88
	v_cmp_le_u32_e32 vcc, v88, v89
	v_add_u32_e32 v91, 1, v88
	v_add_u32_e32 v93, 2, v88
	v_cndmask_b32_e32 v90, v246, v100, vcc
	v_cmp_le_u32_e32 vcc, v91, v89
	v_add_u32_e32 v94, 3, v88
	v_add_u32_e32 v95, 16, v88
	v_cndmask_b32_e32 v91, v246, v101, vcc
	v_cmp_le_u32_e32 vcc, v93, v89
	v_add_u32_e32 v96, 17, v88
	v_add_u32_e32 v97, 18, v88
	v_cndmask_b32_e32 v93, v246, v102, vcc
	v_cmp_le_u32_e32 vcc, v94, v89
	v_add_u32_e32 v98, 19, v88
	v_add_u32_e32 v99, 32, v88
	v_cndmask_b32_e32 v94, v246, v103, vcc
	v_cmp_le_u32_e32 vcc, v95, v89
	v_add_u32_e32 v100, 33, v88
	v_add_u32_e32 v101, 34, v88
	v_cndmask_b32_e32 v95, v246, v104, vcc
	v_cmp_le_u32_e32 vcc, v96, v89
	v_add_u32_e32 v102, 35, v88
	v_add_u32_e32 v103, 48, v88
	v_cndmask_b32_e32 v96, v246, v105, vcc
	v_cmp_le_u32_e32 vcc, v97, v89
	v_add_u32_e32 v104, 49, v88
	v_add_u32_e32 v105, 50, v88
	v_cndmask_b32_e32 v97, v246, v106, vcc
	v_cmp_le_u32_e32 vcc, v98, v89
	v_add_u32_e32 v106, 51, v88
	s_mov_b32 s0, 0xff61b1e6
	v_cndmask_b32_e32 v98, v246, v107, vcc
	v_cmp_le_u32_e32 vcc, v99, v89
	v_add_u32_e32 v107, 64, v88
	v_max3_f32 v92, v90, s0, v91
	v_cndmask_b32_e32 v99, v246, v108, vcc
	v_cmp_le_u32_e32 vcc, v100, v89
	v_add_u32_e32 v108, 0x41, v88
	v_max3_f32 v92, v92, v93, v94
	v_cndmask_b32_e32 v100, v246, v109, vcc
	v_cmp_le_u32_e32 vcc, v101, v89
	v_add_u32_e32 v109, 0x42, v88
	v_max3_f32 v92, v92, v95, v96
	v_cndmask_b32_e32 v101, v246, v110, vcc
	v_cmp_le_u32_e32 vcc, v102, v89
	v_add_u32_e32 v110, 0x43, v88
	v_max3_f32 v92, v92, v97, v98
	v_cndmask_b32_e32 v102, v246, v111, vcc
	v_cmp_le_u32_e32 vcc, v103, v89
	v_add_u32_e32 v111, 0x50, v88
	v_max3_f32 v92, v92, v99, v100
	v_cndmask_b32_e32 v103, v246, v112, vcc
	v_cmp_le_u32_e32 vcc, v104, v89
	v_add_u32_e32 v112, 0x51, v88
	v_max3_f32 v92, v92, v101, v102
	v_cndmask_b32_e32 v104, v246, v113, vcc
	v_cmp_le_u32_e32 vcc, v105, v89
	v_add_u32_e32 v113, 0x52, v88
	v_max3_f32 v92, v92, v103, v104
	v_cndmask_b32_e32 v105, v246, v114, vcc
	v_cmp_le_u32_e32 vcc, v106, v89
	v_add_u32_e32 v114, 0x53, v88
	s_mul_i32 s0, s23, 0xc000
	v_cndmask_b32_e32 v106, v246, v115, vcc
	v_cmp_le_u32_e32 vcc, v107, v89
	v_add_u32_e32 v115, 0x60, v88
	v_max3_f32 v92, v92, v105, v106
	v_cndmask_b32_e32 v107, v246, v116, vcc
	v_cmp_le_u32_e32 vcc, v108, v89
	v_add_u32_e32 v116, 0x61, v88
	s_add_u32 s0, s0, s28
	v_cndmask_b32_e32 v108, v246, v117, vcc
	v_cmp_le_u32_e32 vcc, v109, v89
	v_add_u32_e32 v117, 0x62, v88
	v_max3_f32 v92, v92, v107, v108
	v_cndmask_b32_e32 v109, v246, v118, vcc
	v_cmp_le_u32_e32 vcc, v110, v89
	v_add_u32_e32 v118, 0x63, v88
	s_addc_u32 s1, s1, s29
	v_cndmask_b32_e32 v110, v246, v119, vcc
	v_cmp_le_u32_e32 vcc, v111, v89
	v_add_u32_e32 v119, 0x70, v88
	v_max3_f32 v92, v92, v109, v110
	v_cndmask_b32_e32 v111, v246, v120, vcc
	v_cmp_le_u32_e32 vcc, v112, v89
	v_add_u32_e32 v120, 0x71, v88
	s_lshl_b32 s2, s22, 7
	v_cndmask_b32_e32 v112, v246, v121, vcc
	v_cmp_le_u32_e32 vcc, v113, v89
	v_add_u32_e32 v121, 0x72, v88
	v_max3_f32 v92, v92, v111, v112
	v_cndmask_b32_e32 v113, v246, v122, vcc
	v_cmp_le_u32_e32 vcc, v114, v89
	v_add_u32_e32 v122, 0x73, v88
	s_nop 0
	v_cndmask_b32_e32 v114, v246, v123, vcc
	v_cmp_le_u32_e32 vcc, v115, v89
	v_max3_f32 v92, v92, v113, v114
	v_add_u32_e32 v123, 0x80, v88
	v_cndmask_b32_e32 v115, v246, v124, vcc
	v_cmp_le_u32_e32 vcc, v116, v89
	s_nop 1
	v_cndmask_b32_e32 v116, v246, v125, vcc
	v_cmp_le_u32_e32 vcc, v117, v89
	v_max3_f32 v92, v92, v115, v116
	s_nop 0
	v_cndmask_b32_e32 v117, v246, v126, vcc
	v_cmp_le_u32_e32 vcc, v118, v89
	s_nop 1
	v_cndmask_b32_e32 v118, v246, v127, vcc
	v_cmp_le_u32_e32 vcc, v119, v89
	v_max3_f32 v92, v92, v117, v118
	s_nop 0
	v_cndmask_b32_e32 v119, v246, v130, vcc
	v_cmp_le_u32_e32 vcc, v120, v89
	s_nop 1
	v_cndmask_b32_e32 v120, v246, v131, vcc
	v_cmp_le_u32_e32 vcc, v121, v89
	v_max3_f32 v92, v92, v119, v120
	s_nop 0
	v_cndmask_b32_e32 v121, v246, v132, vcc
	v_cmp_le_u32_e32 vcc, v122, v89
	s_nop 1
	v_cndmask_b32_e32 v122, v246, v133, vcc
	v_cmp_le_u32_e32 vcc, v123, v89
	v_add_u32_e32 v123, 0x81, v88
	v_max3_f32 v92, v92, v121, v122
	v_cndmask_b32_e32 v84, v246, v84, vcc
	v_cmp_le_u32_e32 vcc, v123, v89
	v_add_u32_e32 v123, 0x82, v88
	v_add_u32_e32 v88, 0x83, v88
	v_cndmask_b32_e32 v85, v246, v85, vcc
	v_cmp_le_u32_e32 vcc, v123, v89
	v_max3_f32 v92, v92, v84, v85
	s_nop 0
	v_cndmask_b32_e32 v86, v246, v86, vcc
	v_cmp_le_u32_e32 vcc, v88, v89
	s_nop 1
	v_cndmask_b32_e32 v87, v246, v87, vcc
	v_max3_f32 v88, v92, v86, v87
	ds_swizzle_b32 v89, v88 offset:swizzle(SWAP,16)
	s_waitcnt lgkmcnt(0)
	v_max_f32_e32 v89, v89, v89
	v_max_f32_e32 v88, v88, v89
	v_mbcnt_lo_u32_b32 v89, -1, 0
	v_mbcnt_hi_u32_b32 v89, -1, v89
	s_nop 0
	v_lshlrev_b32_e32 v89, 2, v89
	v_xor_b32_e32 v89, 0x80, v89
	ds_bpermute_b32 v89, v89, v88
	s_waitcnt lgkmcnt(0)
; __device__ __forceinline__ unsigned pk_h2(float lo, float hi) { f32x2 v = {lo, hi}; h16x2 h = __builtin_convertvector(v, h16x2); return __builtin_bit_cast(unsigned, h); }
; __device__ __forceinline__ void attn_phase(Frame& F, h16* Obr) {
;     ...
;         mx = fmaxf(mx, shx<16>(mx)); mx = fmaxf(mx, shx<32>(mx));
;         float den = 0.f;
; #pragma unroll
;         for (int tt = 0; tt < 9; ++tt)
; #pragma unroll
;             for (int e = 0; e < 4; ++e) { const float pv = __builtin_amdgcn_exp2f(sc[tt][e] - mx); sc[tt][e] = pv; den += pv; }
;         den += shx<16>(den); den += shx<32>(den);
;         h16x8 Pf[5];
; #pragma unroll
;         for (int ks = 0; ks < 5; ++ks) { u32x4 wv; wv.x = pk_h2(sc[2 * ks][0], sc[2 * ks][1]); wv.y = pk_h2(sc[2 * ks][2], sc[2 * ks][3]);
;             if (ks < 4) { wv.z = pk_h2(sc[2 * ks + 1][0], sc[2 * ks + 1][1]); wv.w = pk_h2(sc[2 * ks + 1][2], sc[2 * ks + 1][3]); } else { wv.z = 0u; wv.w = 0u; }
;             Pf[ks] = __builtin_bit_cast(h16x8, wv); }
;         const float rden = 1.0f / den;
;         unsigned char* op = (unsigned char*)Obr + ((size_t)cu.br * M + cu.rowb + qtok) * 1024 + cu.h * 128 + 4 * g;
;         const float rs16 = rden * 16.0f;
;         const int qq = q16 >> 2, pp = q16 & 3;
;         typedef short s16x8 __attribute__((ext_vector_type(8)));
;         s16x4 vlo[2][5], vhi[2][5];
;     ...
;         ATT_LDV(0, 0);
; #pragma unroll
;         for (int c8 = 0; c8 < 8; ++c8) {
;             if (c8 + 1 < 8) ATT_LDV((c8 + 1) & 1, c8 + 1);
;             asm volatile("" ::: "memory");
;             f32x4 o = {0.f, 0.f, 0.f, 0.f};
; #pragma unroll
;             for (int ks = 0; ks < 5; ++ks) {
;                 const s16x8 vv = __builtin_shufflevector(vlo[c8 & 1][ks], vhi[c8 & 1][ks], 0, 1, 2, 3, 4, 5, 6, 7);
;                 o = __builtin_amdgcn_mfma_f32_16x16x32_f16(__builtin_bit_cast(h16x8, vv), Pf[ks], o, 0, 0, 0); }
;             int ov = __builtin_amdgcn_cvt_pk_fp8_f32(o[0] * rs16, o[1] * rs16, 0, false); ov = __builtin_amdgcn_cvt_pk_fp8_f32(o[2] * rs16, o[3] * rs16, ov, true);
	v_max_f32_e32 v89, v89, v89
	v_max_f32_e32 v194, v88, v89
	v_sub_f32_e32 v88, v90, v194
	v_exp_f32_e32 v88, v88
	v_sub_f32_e32 v90, v91, v194
	v_exp_f32_e32 v90, v90
	v_sub_f32_e32 v91, v93, v194
	v_exp_f32_e32 v91, v91
	v_sub_f32_e32 v92, v94, v194
	v_exp_f32_e32 v92, v92
	v_sub_f32_e32 v93, v95, v194
	v_add_f32_e32 v89, 0, v88
	v_exp_f32_e32 v93, v93
	v_sub_f32_e32 v94, v96, v194
	v_add_f32_e32 v89, v90, v89
	v_exp_f32_e32 v94, v94
	v_sub_f32_e32 v95, v97, v194
	v_add_f32_e32 v89, v91, v89
	v_exp_f32_e32 v95, v95
	v_sub_f32_e32 v96, v98, v194
	v_add_f32_e32 v89, v92, v89
	v_exp_f32_e32 v96, v96
	v_sub_f32_e32 v97, v99, v194
	v_add_f32_e32 v89, v93, v89
	v_exp_f32_e32 v97, v97
	v_sub_f32_e32 v98, v100, v194
	v_add_f32_e32 v89, v94, v89
	v_exp_f32_e32 v98, v98
	v_sub_f32_e32 v99, v101, v194
	v_add_f32_e32 v89, v95, v89
	v_exp_f32_e32 v99, v99
	v_sub_f32_e32 v100, v102, v194
	v_add_f32_e32 v89, v96, v89
	v_exp_f32_e32 v123, v100
	v_sub_f32_e32 v100, v103, v194
	v_add_f32_e32 v89, v97, v89
	v_exp_f32_e32 v124, v100
	v_sub_f32_e32 v100, v104, v194
	v_add_f32_e32 v89, v98, v89
	v_exp_f32_e32 v104, v100
	v_sub_f32_e32 v100, v105, v194
	v_add_f32_e32 v89, v99, v89
	v_exp_f32_e32 v105, v100
	v_sub_f32_e32 v100, v106, v194
	v_add_f32_e32 v89, v123, v89
	v_exp_f32_e32 v106, v100
	v_sub_f32_e32 v100, v107, v194
	v_add_f32_e32 v89, v124, v89
	v_exp_f32_e32 v107, v100
	v_sub_f32_e32 v100, v108, v194
	v_add_f32_e32 v89, v104, v89
	v_exp_f32_e32 v108, v100
	v_sub_f32_e32 v100, v109, v194
	v_add_f32_e32 v89, v105, v89
	v_exp_f32_e32 v109, v100
	v_sub_f32_e32 v100, v110, v194
	v_add_f32_e32 v89, v106, v89
	v_exp_f32_e32 v110, v100
	v_sub_f32_e32 v100, v111, v194
	v_add_f32_e32 v89, v107, v89
	v_exp_f32_e32 v111, v100
	v_sub_f32_e32 v100, v112, v194
	v_add_f32_e32 v89, v108, v89
	v_exp_f32_e32 v112, v100
	v_sub_f32_e32 v100, v113, v194
	v_add_f32_e32 v89, v109, v89
	v_exp_f32_e32 v113, v100
	v_sub_f32_e32 v100, v114, v194
	v_add_f32_e32 v89, v110, v89
	v_exp_f32_e32 v114, v100
	v_sub_f32_e32 v100, v115, v194
	v_add_f32_e32 v89, v111, v89
	v_exp_f32_e32 v115, v100
	v_sub_f32_e32 v100, v116, v194
	v_add_f32_e32 v89, v112, v89
	v_exp_f32_e32 v116, v100
	v_sub_f32_e32 v100, v117, v194
	v_add_f32_e32 v89, v113, v89
	v_exp_f32_e32 v117, v100
	v_sub_f32_e32 v100, v118, v194
	v_add_f32_e32 v89, v114, v89
	v_exp_f32_e32 v118, v100
	v_sub_f32_e32 v100, v119, v194
	v_add_f32_e32 v89, v115, v89
	v_exp_f32_e32 v119, v100
	v_sub_f32_e32 v100, v120, v194
	v_add_f32_e32 v89, v116, v89
	v_exp_f32_e32 v120, v100
	v_sub_f32_e32 v100, v121, v194
	v_add_f32_e32 v89, v117, v89
	v_exp_f32_e32 v121, v100
	v_sub_f32_e32 v100, v122, v194
	v_add_f32_e32 v89, v118, v89
	v_exp_f32_e32 v122, v100
	v_sub_f32_e32 v84, v84, v194
	v_add_f32_e32 v89, v119, v89
	v_exp_f32_e32 v84, v84
	v_sub_f32_e32 v85, v85, v194
	v_add_f32_e32 v89, v120, v89
	v_exp_f32_e32 v85, v85
	v_sub_f32_e32 v86, v86, v194
	v_add_f32_e32 v89, v121, v89
	v_exp_f32_e32 v86, v86
	v_sub_f32_e32 v87, v87, v194
	v_add_f32_e32 v89, v122, v89
	v_exp_f32_e32 v87, v87
	v_add_f32_e32 v89, v84, v89
	v_add_f32_e32 v89, v85, v89
	v_add_f32_e32 v89, v86, v89
	v_add_f32_e32 v89, v87, v89
	ds_swizzle_b32 v100, v89 offset:swizzle(SWAP,16)
	v_cvt_pk_f16_f32 v103, v95, v96
	v_cvt_pk_f16_f32 v96, v97, v98
	v_cvt_pk_f16_f32 v98, v124, v104
	v_add_u32_e32 v104, s49, v128
	s_waitcnt lgkmcnt(0)
	v_add_f32_e32 v125, v89, v100
	v_mbcnt_lo_u32_b32 v89, -1, 0
	v_mbcnt_hi_u32_b32 v89, -1, v89
	v_cvt_pk_f16_f32 v97, v99, v123
	v_lshlrev_b32_e32 v89, 2, v89
	v_xor_b32_e32 v89, 0x80, v89
	ds_bpermute_b32 v126, v89, v125
	v_cvt_pk_f16_f32 v99, v105, v106
	v_ashrrev_i32_e32 v105, 31, v104
	v_cvt_pk_f16_f32 v100, v88, v90
	v_cvt_pk_f16_f32 v101, v91, v92
	v_cvt_pk_f16_f32 v102, v93, v94
	v_cvt_pk_f16_f32 v94, v111, v112
	v_cvt_pk_f16_f32 v95, v113, v114
	v_cvt_pk_f16_f32 v88, v115, v116
	v_cvt_pk_f16_f32 v89, v117, v118
	v_cvt_pk_f16_f32 v90, v119, v120
	s_waitcnt lgkmcnt(0)
	v_add_f32_e32 v195, v125, v126
	v_lshl_add_u64 v[152:153], s[0:1], 0, v[104:105]
	ds_read_b64_tr_b16 v[112:113], v178
	ds_read_b64_tr_b16 v[114:115], v179 offset:4096
	ds_read_b64_tr_b16 v[116:117], v178 offset:8192
	ds_read_b64_tr_b16 v[118:119], v179 offset:12288
	ds_read_b64_tr_b16 v[124:125], v178 offset:16384
	ds_read_b64_tr_b16 v[126:127], v179 offset:20480
	ds_read_b64_tr_b16 v[132:133], v178 offset:24576
	ds_read_b64_tr_b16 v[134:135], v179 offset:28672
	ds_read_b64_tr_b16 v[136:137], v178 offset:32768
	ds_read_b64_tr_b16 v[138:139], v179 offset:36864
	v_lshlrev_b64 v[104:105], 10, v[152:153]
	s_waitcnt lgkmcnt(8)
	v_mfma_f32_16x16x32_f16 v[112:115], v[112:115], v[100:103], 0
	v_lshl_add_u64 v[104:105], s[6:7], 0, v[104:105]
	v_lshl_add_u64 v[104:105], v[104:105], 0, s[2:3]
	v_lshl_add_u64 v[154:155], v[104:105], 0, v[150:151]
	v_div_scale_f32 v104, s[0:1], v195, v195, 1.0
	v_rcp_f32_e32 v105, v104
	s_waitcnt lgkmcnt(6)
	v_mfma_f32_16x16x32_f16 v[112:115], v[116:119], v[96:99], v[112:115]
	v_cvt_pk_f16_f32 v92, v107, v108
	v_cvt_pk_f16_f32 v93, v109, v110
	v_fma_f32 v106, -v104, v105, 1.0
	v_fmac_f32_e32 v105, v106, v105
	s_waitcnt lgkmcnt(4)
	v_mfma_f32_16x16x32_f16 v[112:115], v[124:127], v[92:95], v[112:115]
	v_div_scale_f32 v106, vcc, 1.0, v195, 1.0
	v_mul_f32_e32 v107, v106, v105
	v_cvt_pk_f16_f32 v91, v121, v122
	v_fma_f32 v108, -v104, v107, v106
	v_fmac_f32_e32 v107, v108, v105
	s_waitcnt lgkmcnt(2)
; __device__ __forceinline__ void attn_phase(Frame& F, h16* Obr) {
;     ...
;         const float rden = 1.0f / den;
;         unsigned char* op = (unsigned char*)Obr + ((size_t)cu.br * M + cu.rowb + qtok) * 1024 + cu.h * 128 + 4 * g;
;         const float rs16 = rden * 16.0f;
;         const int qq = q16 >> 2, pp = q16 & 3;
;         typedef short s16x8 __attribute__((ext_vector_type(8)));
;         s16x4 vlo[2][5], vhi[2][5];
;     ...
;         ATT_LDV(0, 0);
; #pragma unroll
;         for (int c8 = 0; c8 < 8; ++c8) {
;             if (c8 + 1 < 8) ATT_LDV((c8 + 1) & 1, c8 + 1);
;             asm volatile("" ::: "memory");
;             f32x4 o = {0.f, 0.f, 0.f, 0.f};
; #pragma unroll
;             for (int ks = 0; ks < 5; ++ks) {
;                 const s16x8 vv = __builtin_shufflevector(vlo[c8 & 1][ks], vhi[c8 & 1][ks], 0, 1, 2, 3, 4, 5, 6, 7);
;                 o = __builtin_amdgcn_mfma_f32_16x16x32_f16(__builtin_bit_cast(h16x8, vv), Pf[ks], o, 0, 0, 0); }
;             int ov = __builtin_amdgcn_cvt_pk_fp8_f32(o[0] * rs16, o[1] * rs16, 0, false); ov = __builtin_amdgcn_cvt_pk_fp8_f32(o[2] * rs16, o[3] * rs16, ov, true);
;             *(int*)(op + 16 * c8) = ov; }
	v_mfma_f32_16x16x32_f16 v[112:115], v[132:135], v[88:91], v[112:115]
	v_fma_f32 v104, -v104, v107, v106
	v_div_fmas_f32 v104, v104, v105, v107
	v_cvt_pk_f16_f32 v84, v84, v85
	v_cvt_pk_f16_f32 v85, v86, v87
	v_mov_b32_e32 v86, v209
	v_mov_b32_e32 v87, v209
	v_div_fixup_f32 v104, v104, v195, 1.0
	v_mul_f32_e32 v196, 0x41800000, v104
	ds_read_b64_tr_b16 v[140:141], v180
	ds_read_b64_tr_b16 v[142:143], v181 offset:4096
	ds_read_b64_tr_b16 v[128:129], v180 offset:8192
	ds_read_b64_tr_b16 v[130:131], v181 offset:12288
	ds_read_b64_tr_b16 v[120:121], v180 offset:16384
	ds_read_b64_tr_b16 v[122:123], v181 offset:20480
	ds_read_b64_tr_b16 v[108:109], v180 offset:24576
	ds_read_b64_tr_b16 v[110:111], v181 offset:28672
	ds_read_b64_tr_b16 v[104:105], v180 offset:32768
	ds_read_b64_tr_b16 v[106:107], v181 offset:36864
	s_waitcnt lgkmcnt(10)
	v_mfma_f32_16x16x32_f16 v[112:115], v[136:139], v[84:87], v[112:115]
	v_mov_b32_e32 v116, v209
	s_waitcnt lgkmcnt(8)
	v_mfma_f32_16x16x32_f16 v[136:139], v[140:143], v[100:103], 0
	s_waitcnt lgkmcnt(6)
	v_mfma_f32_16x16x32_f16 v[128:131], v[128:131], v[96:99], v[136:139]
	s_nop 2
	v_mul_f32_e32 v112, v112, v196
	v_mul_f32_e32 v113, v113, v196
	v_cvt_pk_fp8_f32 v116, v112, v113
	s_waitcnt lgkmcnt(4)
	v_mfma_f32_16x16x32_f16 v[120:123], v[120:123], v[92:95], v[128:131]
	v_mul_f32_e32 v112, v114, v196
	v_mul_f32_e32 v113, v115, v196
	v_cvt_pk_fp8_f32 v116, v112, v113 op_sel:[0,0,1]
	s_waitcnt lgkmcnt(2)
	v_mfma_f32_16x16x32_f16 v[108:111], v[108:111], v[88:91], v[120:123]
	global_store_dword v[154:155], v116, off
	s_waitcnt lgkmcnt(0)
	v_mfma_f32_16x16x32_f16 v[104:107], v[104:107], v[84:87], v[108:111]
	ds_read_b64_tr_b16 v[132:133], v182
	ds_read_b64_tr_b16 v[134:135], v183 offset:4096
	ds_read_b64_tr_b16 v[144:145], v182 offset:8192
	ds_read_b64_tr_b16 v[146:147], v183 offset:12288
	ds_read_b64_tr_b16 v[124:125], v182 offset:16384
	ds_read_b64_tr_b16 v[126:127], v183 offset:20480
	ds_read_b64_tr_b16 v[116:117], v182 offset:24576
	ds_read_b64_tr_b16 v[118:119], v183 offset:28672
	ds_read_b64_tr_b16 v[112:113], v182 offset:32768
	ds_read_b64_tr_b16 v[114:115], v183 offset:36864
	v_mov_b32_e32 v108, v209
	v_mul_f32_e32 v104, v196, v104
	v_mul_f32_e32 v105, v196, v105
	v_cvt_pk_fp8_f32 v108, v104, v105
	v_mul_f32_e32 v104, v196, v106
	v_mul_f32_e32 v105, v196, v107
	v_cvt_pk_fp8_f32 v108, v104, v105 op_sel:[0,0,1]
	s_waitcnt lgkmcnt(8)
	v_mfma_f32_16x16x32_f16 v[104:107], v[132:135], v[100:103], 0
	global_store_dword v[154:155], v108, off offset:16
	s_waitcnt lgkmcnt(6)
	v_mfma_f32_16x16x32_f16 v[104:107], v[144:147], v[96:99], v[104:107]
	ds_read_b64_tr_b16 v[140:141], v184
	ds_read_b64_tr_b16 v[142:143], v185 offset:4096
	ds_read_b64_tr_b16 v[136:137], v184 offset:8192
	ds_read_b64_tr_b16 v[138:139], v185 offset:12288
	ds_read_b64_tr_b16 v[128:129], v184 offset:16384
	ds_read_b64_tr_b16 v[130:131], v185 offset:20480
	ds_read_b64_tr_b16 v[120:121], v184 offset:24576
	ds_read_b64_tr_b16 v[122:123], v185 offset:28672
	ds_read_b64_tr_b16 v[108:109], v184 offset:32768
	ds_read_b64_tr_b16 v[110:111], v185 offset:36864
	s_waitcnt lgkmcnt(14)
	v_mfma_f32_16x16x32_f16 v[104:107], v[124:127], v[92:95], v[104:107]
	s_waitcnt lgkmcnt(12)
	v_mfma_f32_16x16x32_f16 v[104:107], v[116:119], v[88:91], v[104:107]
	s_waitcnt lgkmcnt(10)
	v_mfma_f32_16x16x32_f16 v[104:107], v[112:115], v[84:87], v[104:107]
	v_mov_b32_e32 v112, v209
	s_nop 6
	v_mul_f32_e32 v104, v196, v104
	v_mul_f32_e32 v105, v196, v105
	v_cvt_pk_fp8_f32 v112, v104, v105
	v_mul_f32_e32 v104, v196, v106
	v_mul_f32_e32 v105, v196, v107
	v_cvt_pk_fp8_f32 v112, v104, v105 op_sel:[0,0,1]
	global_store_dword v[154:155], v112, off offset:32
	s_waitcnt lgkmcnt(8)
	v_mfma_f32_16x16x32_f16 v[112:115], v[140:143], v[100:103], 0
	ds_read_b64_tr_b16 v[144:145], v186
	ds_read_b64_tr_b16 v[146:147], v187 offset:4096
	ds_read_b64_tr_b16 v[132:133], v186 offset:8192
	ds_read_b64_tr_b16 v[134:135], v187 offset:12288
	ds_read_b64_tr_b16 v[124:125], v186 offset:16384
	ds_read_b64_tr_b16 v[126:127], v187 offset:20480
	ds_read_b64_tr_b16 v[116:117], v186 offset:24576
	ds_read_b64_tr_b16 v[118:119], v187 offset:28672
	ds_read_b64_tr_b16 v[104:105], v186 offset:32768
	ds_read_b64_tr_b16 v[106:107], v187 offset:36864
	s_waitcnt lgkmcnt(14)
	v_mfma_f32_16x16x32_f16 v[112:115], v[136:139], v[96:99], v[112:115]
	v_mfma_f32_16x16x32_f16 v[112:115], v[128:131], v[92:95], v[112:115]
	s_waitcnt lgkmcnt(12)
	v_mfma_f32_16x16x32_f16 v[112:115], v[120:123], v[88:91], v[112:115]
	s_waitcnt lgkmcnt(10)
	v_mfma_f32_16x16x32_f16 v[108:111], v[108:111], v[84:87], v[112:115]
	s_nop 5
	v_mov_b32_e32 v112, v209
	s_nop 0
	v_mul_f32_e32 v108, v196, v108
	v_mul_f32_e32 v109, v196, v109
	v_cvt_pk_fp8_f32 v112, v108, v109
	v_mul_f32_e32 v108, v196, v110
	v_mul_f32_e32 v109, v196, v111
	v_cvt_pk_fp8_f32 v112, v108, v109 op_sel:[0,0,1]
	s_waitcnt lgkmcnt(8)
; __device__ __forceinline__ void attn_phase(Frame& F, h16* Obr) {
;     ...
;         for (int c8 = 0; c8 < 8; ++c8) {
;             if (c8 + 1 < 8) ATT_LDV((c8 + 1) & 1, c8 + 1);
;             asm volatile("" ::: "memory");
;             f32x4 o = {0.f, 0.f, 0.f, 0.f};
; #pragma unroll
;             for (int ks = 0; ks < 5; ++ks) {
;                 const s16x8 vv = __builtin_shufflevector(vlo[c8 & 1][ks], vhi[c8 & 1][ks], 0, 1, 2, 3, 4, 5, 6, 7);
;                 o = __builtin_amdgcn_mfma_f32_16x16x32_f16(__builtin_bit_cast(h16x8, vv), Pf[ks], o, 0, 0, 0); }
;             int ov = __builtin_amdgcn_cvt_pk_fp8_f32(o[0] * rs16, o[1] * rs16, 0, false); ov = __builtin_amdgcn_cvt_pk_fp8_f32(o[2] * rs16, o[3] * rs16, ov, true);
;             *(int*)(op + 16 * c8) = ov; }
;     ...
;         if (g == 0) Lse[((size_t)cu.br * M + cu.rowb + qtok) * 8 + cu.h] = (mx + __log2f(den)) * 0.69314718055994531f;
	v_mfma_f32_16x16x32_f16 v[108:111], v[144:147], v[100:103], 0
	global_store_dword v[154:155], v112, off offset:48
	ds_read_b64_tr_b16 v[140:141], v188
	ds_read_b64_tr_b16 v[142:143], v189 offset:4096
	ds_read_b64_tr_b16 v[136:137], v188 offset:8192
	ds_read_b64_tr_b16 v[138:139], v189 offset:12288
	ds_read_b64_tr_b16 v[128:129], v188 offset:16384
	ds_read_b64_tr_b16 v[130:131], v189 offset:20480
	ds_read_b64_tr_b16 v[120:121], v188 offset:24576
	ds_read_b64_tr_b16 v[122:123], v189 offset:28672
	ds_read_b64_tr_b16 v[112:113], v188 offset:32768
	ds_read_b64_tr_b16 v[114:115], v189 offset:36864
	s_waitcnt lgkmcnt(14)
	v_mfma_f32_16x16x32_f16 v[108:111], v[132:135], v[96:99], v[108:111]
	s_waitcnt lgkmcnt(8)
	v_mfma_f32_16x16x32_f16 v[140:143], v[140:143], v[100:103], 0
	v_mfma_f32_16x16x32_f16 v[108:111], v[124:127], v[92:95], v[108:111]
	s_waitcnt lgkmcnt(6)
	v_mfma_f32_16x16x32_f16 v[136:139], v[136:139], v[96:99], v[140:143]
	v_mfma_f32_16x16x32_f16 v[108:111], v[116:119], v[88:91], v[108:111]
	s_waitcnt lgkmcnt(4)
	v_mfma_f32_16x16x32_f16 v[128:131], v[128:131], v[92:95], v[136:139]
	v_mfma_f32_16x16x32_f16 v[104:107], v[104:107], v[84:87], v[108:111]
	s_waitcnt lgkmcnt(2)
	v_mfma_f32_16x16x32_f16 v[120:123], v[120:123], v[88:91], v[128:131]
	s_nop 2
	v_mov_b32_e32 v108, v209
	s_nop 1
	v_mul_f32_e32 v104, v196, v104
	v_mul_f32_e32 v105, v196, v105
	v_cvt_pk_fp8_f32 v108, v104, v105
	s_waitcnt lgkmcnt(0)
	v_mfma_f32_16x16x32_f16 v[112:115], v[112:115], v[84:87], v[120:123]
	v_mul_f32_e32 v104, v196, v106
	v_mul_f32_e32 v105, v196, v107
	v_cvt_pk_fp8_f32 v108, v104, v105 op_sel:[0,0,1]
	v_mov_b32_e32 v120, v209
	global_store_dword v[154:155], v108, off offset:64
	s_nop 2
	v_mul_f32_e32 v112, v196, v112
	v_mul_f32_e32 v113, v196, v113
	v_cvt_pk_fp8_f32 v120, v112, v113
	v_mul_f32_e32 v112, v196, v114
	v_mul_f32_e32 v113, v196, v115
	ds_read_b64_tr_b16 v[132:133], v190
	ds_read_b64_tr_b16 v[134:135], v191 offset:4096
	ds_read_b64_tr_b16 v[124:125], v190 offset:8192
	ds_read_b64_tr_b16 v[126:127], v191 offset:12288
	ds_read_b64_tr_b16 v[116:117], v190 offset:16384
	ds_read_b64_tr_b16 v[118:119], v191 offset:20480
	ds_read_b64_tr_b16 v[108:109], v190 offset:24576
	ds_read_b64_tr_b16 v[110:111], v191 offset:28672
	ds_read_b64_tr_b16 v[104:105], v190 offset:32768
	ds_read_b64_tr_b16 v[106:107], v191 offset:36864
	v_cvt_pk_fp8_f32 v120, v112, v113 op_sel:[0,0,1]
	s_waitcnt lgkmcnt(8)
	v_mfma_f32_16x16x32_f16 v[132:135], v[132:135], v[100:103], 0
	global_store_dword v[154:155], v120, off offset:80
	ds_read_b64_tr_b16 v[140:141], v192
	ds_read_b64_tr_b16 v[142:143], v193 offset:4096
	ds_read_b64_tr_b16 v[136:137], v192 offset:8192
	ds_read_b64_tr_b16 v[138:139], v193 offset:12288
	ds_read_b64_tr_b16 v[128:129], v192 offset:16384
	ds_read_b64_tr_b16 v[130:131], v193 offset:20480
	ds_read_b64_tr_b16 v[120:121], v192 offset:24576
	ds_read_b64_tr_b16 v[122:123], v193 offset:28672
	ds_read_b64_tr_b16 v[112:113], v192 offset:32768
	ds_read_b64_tr_b16 v[114:115], v193 offset:36864
	s_waitcnt lgkmcnt(14)
	v_mfma_f32_16x16x32_f16 v[124:127], v[124:127], v[96:99], v[132:135]
	s_waitcnt lgkmcnt(8)
	v_mfma_f32_16x16x32_f16 v[100:103], v[140:143], v[100:103], 0
	v_mfma_f32_16x16x32_f16 v[116:119], v[116:119], v[92:95], v[124:127]
	s_waitcnt lgkmcnt(6)
	v_mfma_f32_16x16x32_f16 v[96:99], v[136:139], v[96:99], v[100:103]
	v_mfma_f32_16x16x32_f16 v[108:111], v[108:111], v[88:91], v[116:119]
	s_waitcnt lgkmcnt(4)
	v_mfma_f32_16x16x32_f16 v[92:95], v[128:131], v[92:95], v[96:99]
	v_mfma_f32_16x16x32_f16 v[104:107], v[104:107], v[84:87], v[108:111]
	s_waitcnt lgkmcnt(2)
	v_mfma_f32_16x16x32_f16 v[88:91], v[120:123], v[88:91], v[92:95]
	s_nop 2
	v_mov_b32_e32 v108, v209
	s_nop 1
	v_mul_f32_e32 v104, v196, v104
	v_mul_f32_e32 v105, v196, v105
	s_waitcnt lgkmcnt(0)
	v_mfma_f32_16x16x32_f16 v[84:87], v[112:115], v[84:87], v[88:91]
	v_cvt_pk_fp8_f32 v108, v104, v105
	v_mul_f32_e32 v104, v196, v106
	v_mul_f32_e32 v105, v196, v107
	v_mov_b32_e32 v88, v209
	v_cvt_pk_fp8_f32 v108, v104, v105 op_sel:[0,0,1]
	s_nop 2
	v_mul_f32_e32 v84, v196, v84
	v_mul_f32_e32 v85, v196, v85
	v_cvt_pk_fp8_f32 v88, v84, v85
	v_mul_f32_e32 v84, v196, v86
	v_mul_f32_e32 v85, v196, v87
	global_store_dword v[154:155], v108, off offset:96
	v_cvt_pk_fp8_f32 v88, v84, v85 op_sel:[0,0,1]
	global_store_dword v[154:155], v88, off offset:112
	s_and_saveexec_b64 s[28:29], s[38:39]
	s_cbranch_execz .LBB0_722
	v_log_f32_e32 v84, v195
	v_readlane_b32 s0, v252, 5
	v_readlane_b32 s1, v252, 6
	s_mov_b32 s23, s3
	v_add_f32_e32 v84, v194, v84
	v_mul_f32_e32 v86, 0x3f317218, v84
	v_lshlrev_b64 v[84:85], 5, v[152:153]
	v_lshl_add_u64 v[84:85], s[0:1], 0, v[84:85]
	v_lshl_add_u64 v[84:85], s[22:23], 2, v[84:85]
	global_store_dword v[84:85], v86, off
	s_branch .LBB0_722

; __global__ void __launch_bounds__(512, 2) mk_fwd(Args args) {
;     extern __shared__ __attribute__((aligned(16))) unsigned char lds_raw[];
	.amdhsa_kernel _Z6mk_fwd4Args
		.amdhsa_group_segment_fixed_size 0
		.amdhsa_private_segment_fixed_size 0
		.amdhsa_kernarg_size 384
		.amdhsa_user_sgpr_count 2
		.amdhsa_user_sgpr_dispatch_ptr 0
		.amdhsa_user_sgpr_queue_ptr 0
		.amdhsa_user_sgpr_kernarg_segment_ptr 1
		.amdhsa_user_sgpr_dispatch_id 0
		.amdhsa_user_sgpr_kernarg_preload_length 0
		.amdhsa_user_sgpr_kernarg_preload_offset 0
		.amdhsa_user_sgpr_private_segment_size 0
		.amdhsa_uses_dynamic_stack 0
		.amdhsa_enable_private_segment 0
		.amdhsa_system_sgpr_workgroup_id_x 1
		.amdhsa_system_sgpr_workgroup_id_y 0
		.amdhsa_system_sgpr_workgroup_id_z 0
		.amdhsa_system_sgpr_workgroup_info 0
		.amdhsa_system_vgpr_workitem_id 0
		.amdhsa_next_free_vgpr 256
		.amdhsa_next_free_sgpr 102
		.amdhsa_accum_offset 256
		.amdhsa_reserve_vcc 1
		.amdhsa_float_round_mode_32 0
		.amdhsa_float_round_mode_16_64 0
		.amdhsa_float_denorm_mode_32 3
		.amdhsa_float_denorm_mode_16_64 3
		.amdhsa_dx10_clamp 1
		.amdhsa_ieee_mode 1
		.amdhsa_fp16_overflow 0
		.amdhsa_tg_split 0
		.amdhsa_exception_fp_ieee_invalid_op 0
		.amdhsa_exception_fp_denorm_src 0
		.amdhsa_exception_fp_ieee_div_zero 0
		.amdhsa_exception_fp_ieee_overflow 0
		.amdhsa_exception_fp_ieee_underflow 0
		.amdhsa_exception_fp_ieee_inexact 0
		.amdhsa_exception_int_div_zero 0
	.end_amdhsa_kernel

; __global__ void __launch_bounds__(512, 2) mk_fwd(Args args) {
;     extern __shared__ __attribute__((aligned(16))) unsigned char lds_raw[];
amdhsa.kernels:
  - .agpr_count:     0
    .args:
      - .offset:         0
        .size:           128
        .value_kind:     by_value
      - .offset:         128
        .size:           4
        .value_kind:     hidden_block_count_x
      - .offset:         132
        .size:           4
        .value_kind:     hidden_block_count_y
      - .offset:         136
        .size:           4
        .value_kind:     hidden_block_count_z
      - .offset:         140
        .size:           2
        .value_kind:     hidden_group_size_x
      - .offset:         142
        .size:           2
        .value_kind:     hidden_group_size_y
      - .offset:         144
        .size:           2
        .value_kind:     hidden_group_size_z
      - .offset:         146
        .size:           2
        .value_kind:     hidden_remainder_x
      - .offset:         148
        .size:           2
        .value_kind:     hidden_remainder_y
      - .offset:         150
        .size:           2
        .value_kind:     hidden_remainder_z
      - .offset:         168
        .size:           8
        .value_kind:     hidden_global_offset_x
      - .offset:         176
        .size:           8
        .value_kind:     hidden_global_offset_y
      - .offset:         184
        .size:           8
        .value_kind:     hidden_global_offset_z
      - .offset:         192
        .size:           2
        .value_kind:     hidden_grid_dims
      - .offset:         248
        .size:           4
        .value_kind:     hidden_dynamic_lds_size
    .group_segment_fixed_size: 0
    .kernarg_segment_align: 8
    .kernarg_segment_size: 384
    .language:       OpenCL C
    .language_version:
      - 2
      - 0
    .max_flat_workgroup_size: 512
    .name:           _Z6mk_fwd4Args
    .private_segment_fixed_size: 0
    .sgpr_count:     108
    .sgpr_spill_count: 261
    .symbol:         _Z6mk_fwd4Args.kd
    .uniform_work_group_size: 1
    .uses_dynamic_stack: false
    .vgpr_count:     256
    .vgpr_spill_count: 0
    .wavefront_size: 64
